# redundant cooperative-groups grid sync (layer 0 phase 0) skipped; XCD grid barrier right after it remains
# speedup vs baseline: 1.0012x; 1.0012x over previous
; __global__ void __launch_bounds__(NT, 2) mk_fwd(Params P) {
;     ...
;             if (l == 0 && st == 0) grid.sync();
;             xcd_barrier(xbar);
.LBB0_941:
	s_branch .LBB0_953
	s_waitcnt vmcnt(0)
	s_barrier
	s_mov_b64 s[0:1], exec
	v_readlane_b32 s2, v254, 54
	v_readlane_b32 s3, v254, 55
	s_and_b64 s[2:3], s[0:1], s[2:3]
	s_mov_b64 exec, s[2:3]
	s_cbranch_execz .LBB0_952
	v_readlane_b32 s2, v252, 1
	v_readlane_b32 s3, v252, 2
	buffer_wbl2 sc1
	s_load_dwordx2 s[2:3], s[2:3], 0x58
	s_mov_b64 s[6:7], exec
	v_mbcnt_lo_u32_b32 v2, s6, 0
	v_mbcnt_hi_u32_b32 v2, s7, v2
	v_cmp_eq_u32_e32 vcc, 0, v2
	s_waitcnt lgkmcnt(0)
	global_load_dword v0, v1, s[2:3] offset:40
	s_and_saveexec_b64 s[26:27], vcc
	s_cbranch_execz .LBB0_945
	s_bcnt1_i32_b64 s5, s[6:7]
	v_mov_b32_e32 v3, s5
	global_atomic_add v3, v1, v3, s[2:3] offset:32 sc0
